# SSD items on blocks 0..255 (one SSD block per CU); steady-ring PEER gather loops; layer-1 norm1 fused after layer-0 PEER
# speedup vs baseline: 1.2003x; 1.0170x over previous
; DI int TID() { int t = threadIdx.x; asm volatile("" : "+v"(t)); return t; }
; DI void phase_norm(const Params& p, int l, int which, int bid, int nblk) {
;   const int lane = TID() & 63, w = TID() >> 6;
;   const float* g = (which ? p.in[I_G2] : p.in[I_G1]) + l * 1024;
;   const bool from_input = (which == 0 && l == 0);
;   for (int row = bid * 4 + w; row < ROWS; row += nblk * 4) {
;     const int b = row / TPB, pos = row % TPB;
;     if (which == 1 && l == 1 && pos < CTXL) continue;
;     const float* xr = xrow_ptr(p, from_input, b, pos);
;     const float* mod = WSP(const float, OFF_MOD) + (size_t)(l * 17 + (pos < CTXL ? 16 : b)) * 6144 + which * 3072;
;     float x[16];
; #pragma unroll
;     for (int hh = 0; hh < 2; ++hh) {
;       const float4 a = *(const float4*)(xr + hh * 512 + lane * 8);
;       const float4 c = *(const float4*)(xr + hh * 512 + lane * 8 + 4);
;       x[hh * 8 + 0] = a.x; x[hh * 8 + 1] = a.y; x[hh * 8 + 2] = a.z; x[hh * 8 + 3] = a.w;
;       x[hh * 8 + 4] = c.x; x[hh * 8 + 5] = c.y; x[hh * 8 + 6] = c.z; x[hh * 8 + 7] = c.w;
;     }
;     float ss = 0.f;
; #pragma unroll
;     for (int i = 0; i < 16; ++i) ss += x[i] * x[i];
;     ss = wave_sum(ss);
;     const float rs = rsqrtf(ss * (1.f / 1024.f) + EPSF);
.LBB0_355:
	v_mov_b32_e32 v0, v218
	v_mov_b32_e32 v1, v218
	v_readlane_b32 s0, v255, 58
	v_ashrrev_i32_e32 v1, 6, v1
	s_mul_i32 s11, s24, 17
	v_add_u32_e32 v8, s0, v1
	s_mov_b32 s0, 0x9000
	v_readlane_b32 s1, v255, 59
	v_cmp_gt_i32_e32 vcc, s0, v8
	s_andn2_b64 vcc, vcc, s[70:71]
	s_and_saveexec_b64 s[0:1], vcc
	s_cbranch_execz .LBB0_362
	s_lshl_b32 s86, s24, 10
	v_readlane_b32 s36, v253, 3
	s_lshl_b64 s[34:35], s[86:87], 2
	v_readlane_b32 s48, v253, 15
	v_lshlrev_b32_e32 v0, 3, v0
	v_readlane_b32 s49, v253, 16
	s_add_u32 s34, s48, s34
	v_and_b32_e32 v0, 0x1f8, v0
	v_cmp_lt_i32_e32 vcc, v209, v213
	v_readlane_b32 s16, v254, 8
	s_addc_u32 s35, s49, s35
	v_lshlrev_b32_e32 v172, 2, v0
	v_cndmask_b32_e32 v1, v215, v209, vcc
	v_cmp_lt_i32_e32 vcc, v210, v213
	v_readlane_b32 s17, v254, 9
	v_lshl_add_u64 v[10:11], s[34:35], 0, v[172:173]
	v_lshlrev_b32_e32 v20, 2, v1
	v_cndmask_b32_e32 v1, v215, v210, vcc
	v_cmp_lt_i32_e32 vcc, v225, v213
	s_and_b64 s[34:35], s[16:17], exec
	v_readlane_b32 s16, v253, 21
	v_readlane_b32 s37, v253, 4
	v_readlane_b32 s40, v253, 7
	v_readlane_b32 s41, v253, 8
	v_lshlrev_b32_e32 v21, 2, v1
	v_cndmask_b32_e32 v1, v215, v225, vcc
	v_cmp_lt_i32_e32 vcc, v212, v213
	v_readlane_b32 s17, v253, 22
	v_lshlrev_b32_e32 v22, 2, v1
	v_cndmask_b32_e32 v1, v215, v212, vcc
	v_cmp_lt_i32_e32 vcc, v203, v213
	s_cselect_b32 s35, s37, s95
	s_cselect_b32 s34, s36, s94
	s_cselect_b32 s37, s41, s17
	s_cselect_b32 s36, s40, s16
	v_readlane_b32 s16, v253, 19
	v_lshlrev_b32_e32 v23, 2, v1
	v_cndmask_b32_e32 v1, v215, v203, vcc
	v_cmp_lt_i32_e32 vcc, v224, v213
	v_readlane_b32 s17, v253, 20
	v_readlane_b32 s38, v253, 5
	v_readlane_b32 s39, v253, 6
	v_lshlrev_b32_e32 v24, 2, v1
	v_cndmask_b32_e32 v1, v215, v224, vcc
	v_lshl_add_u64 v[12:13], s[16:17], 0, v[172:173]
	v_lshlrev_b32_e32 v172, 1, v0
	v_lshlrev_b32_e32 v25, 2, v1
	v_lshl_add_u64 v[14:15], s[6:7], 0, v[172:173]
	s_mov_b64 s[38:39], 0
	v_lshlrev_b32_e32 v16, 2, v0
	v_mov_b32_e32 v17, v173
	v_readlane_b32 s42, v253, 9
	v_readlane_b32 s43, v253, 10
	v_readlane_b32 s44, v253, 11
	v_readlane_b32 s45, v253, 12
	v_readlane_b32 s46, v253, 13
	v_readlane_b32 s47, v253, 14
	v_readlane_b32 s50, v253, 17
	v_readlane_b32 s51, v253, 18
	s_branch .LBB0_358

;   if (!(bid & 1)) for (int it = bid >> 1; it < 256; it += (nblk + 1) >> 1) ssd_item(p, l, it, smem);
.LBB0_973:
	s_or_b64 exec, exec, s[0:1]
	v_readlane_b32 s0, v255, 45
	v_readlane_b32 s1, v255, 46
	s_andn2_b64 vcc, exec, s[0:1]
	s_waitcnt lgkmcnt(0)
	s_barrier
	v_readlane_b32 s0, v253, 0
	s_cmpk_lt_u32 s0, 0x100
	s_cbranch_scc0 .LBB0_1125
	s_setprio 3
	s_lshl_b32 s13, s24, 4
	s_mov_b32 s74, s0
	s_branch .LBB0_976

; DI void phase_peer(const Params& p, int l, int bid, int nblk) {
;     ...
;     for (int prep_ = 0; prep_ < PEER_REPS; ++prep_) {
;     f32x2 hv2[8];
; #pragma unroll
;     for (int i = 0; i < 8; ++i) hv2[i] = (f32x2){hv[2 * i], hv[2 * i + 1]};
;     const bool b0 = lane & 1, b1 = lane & 2, b2 = lane & 4;
;     float act0 = 0.f, act1 = 0.f;
;     u32x4 rb[2][8];
;     ...
;     PEER_LOAD(0, 0, UB)
; #pragma unroll 1
;     for (int k = 0; k < 16; k += 2) {
;       PEER_LOAD(1, k + 1, UB)
;       __builtin_amdgcn_sched_barrier(0);
;       PEER_DOT(0, k)
;       { const int kn = (k + 2 < 16) ? k + 2 : 15; PEER_LOAD(0, kn, UB) }
;       __builtin_amdgcn_sched_barrier(0);
;       PEER_DOT(1, k + 1)
;     }
.Lpeer_noskip:
	s_add_u32 s44, s96, 0xea00000
	s_addc_u32 s45, s97, 0
	s_mov_b32 s42, s44
	s_mov_b32 s43, s45
	s_mov_b32 s46, 0
	s_mov_b32 s47, 0
	s_mov_b32 s50, 0
	s_lshl_b32 s49, s75, 3
	s_cmp_ge_u32 s47, s55
	s_addc_u32 s48, s47, 0
	s_cmp_ge_u32 s48, s66
	s_addc_u32 s48, s48, 0
	s_lshl_b32 s48, s48, 11
	s_add_i32 s48, s48, s67
	s_lshl_b32 s51, s48, 11
	s_add_u32 s78, s6, s51
	s_addc_u32 s79, s7, 0
	global_load_dwordx4 v[96:99], v165, s[78:79]
	global_load_dwordx4 v[100:103], v165, s[78:79] offset:16
	v_add_u32_e32 v144, s50, v162
	ds_read_b128 v[64:67], v144
	ds_read_b128 v[68:71], v144 offset:16
	ds_read_b128 v[72:75], v144 offset:32
	ds_read_b128 v[76:79], v144 offset:48
	s_waitcnt lgkmcnt(0)
	v_add_u32_e32 v0, v64, v160
	v_add_u32_e32 v4, v65, v160
	global_load_dwordx4 v[0:3], v0, s[42:43]
	global_load_dwordx4 v[4:7], v4, s[42:43]
	v_add_u32_e32 v8, v66, v160
	v_add_u32_e32 v12, v67, v160
	global_load_dwordx4 v[8:11], v8, s[42:43]
	global_load_dwordx4 v[12:15], v12, s[42:43]
	v_add_u32_e32 v16, v68, v160
	v_add_u32_e32 v20, v69, v160
	global_load_dwordx4 v[16:19], v16, s[42:43]
	global_load_dwordx4 v[20:23], v20, s[42:43]
	v_add_u32_e32 v24, v70, v160
	v_add_u32_e32 v28, v71, v160
	global_load_dwordx4 v[24:27], v24, s[42:43]
	global_load_dwordx4 v[28:31], v28, s[42:43]
	v_add_u32_e32 v32, v72, v160
	v_add_u32_e32 v36, v73, v160
	global_load_dwordx4 v[32:35], v32, s[42:43]
	global_load_dwordx4 v[36:39], v36, s[42:43]
	v_add_u32_e32 v40, v74, v160
	v_add_u32_e32 v44, v75, v160
	global_load_dwordx4 v[40:43], v40, s[42:43]
	global_load_dwordx4 v[44:47], v44, s[42:43]
	v_add_u32_e32 v48, v76, v160
	v_add_u32_e32 v52, v77, v160
	global_load_dwordx4 v[48:51], v48, s[42:43]
	global_load_dwordx4 v[52:55], v52, s[42:43]
	v_add_u32_e32 v56, v78, v160
	v_add_u32_e32 v60, v79, v160
	global_load_dwordx4 v[56:59], v56, s[42:43]
	global_load_dwordx4 v[60:63], v60, s[42:43]
.Lpeer_u_top:
	s_add_i32 s63, s47, 1
	s_cmp_lt_u32 s63, s75
	s_cselect_b32 s63, s63, 0
	s_cselect_b32 s51, 0, 1
	s_add_i32 s62, s46, s51
	s_cmp_lt_u32 s62, 8
	s_cselect_b32 s62, s62, 7
	s_cselect_b32 s63, s63, s47
	s_cmp_ge_u32 s63, s55
	s_addc_u32 s64, s63, 0
	s_cmp_ge_u32 s64, s66
	s_addc_u32 s64, s64, 0
	s_lshl_b32 s64, s64, 11
	s_add_i32 s64, s64, s67
	s_lshl_b32 s65, s63, 9
	s_lshl_b32 s51, s62, 21
	s_add_u32 s42, s44, s51
	s_addc_u32 s43, s45, 0
	s_lshl_b32 s51, s48, 9
	s_add_u32 s80, s96, s51
	s_addc_u32 s81, s97, 0
	s_lshl_b32 s51, s64, 11
	s_add_u32 s78, s6, s51
	s_addc_u32 s79, s7, 0
	s_lshl_b32 s51, s62, 8
	s_add_u32 s78, s78, s51
	s_addc_u32 s79, s79, 0
	s_waitcnt vmcnt(16)
	v_lshlrev_b32_e32 v80, 16, v96
	v_and_b32_e32 v81, 0xffff0000, v96
	v_lshlrev_b32_e32 v82, 16, v97
	v_and_b32_e32 v83, 0xffff0000, v97
	v_lshlrev_b32_e32 v84, 16, v98
	v_and_b32_e32 v85, 0xffff0000, v98
	v_lshlrev_b32_e32 v86, 16, v99
	v_and_b32_e32 v87, 0xffff0000, v99
	v_lshlrev_b32_e32 v88, 16, v100
	v_and_b32_e32 v89, 0xffff0000, v100
	v_lshlrev_b32_e32 v90, 16, v101
	v_and_b32_e32 v91, 0xffff0000, v101
	v_lshlrev_b32_e32 v92, 16, v102
	v_and_b32_e32 v93, 0xffff0000, v102
	v_lshlrev_b32_e32 v94, 16, v103
	v_and_b32_e32 v95, 0xffff0000, v103
	v_add_u32_e32 v144, s65, v162
	ds_read_b128 v[64:67], v144
	ds_read_b128 v[68:71], v144 offset:16
	ds_read_b128 v[72:75], v144 offset:32
	ds_read_b128 v[76:79], v144 offset:48
	v_add_u32_e32 v145, s50, v163
	ds_read2_b32 v[140:141], v145 offset1:8
	global_load_dword v142, v167, s[80:81] sc1
	global_load_dword v143, v167, s[80:81] offset:32 sc1
	global_load_dwordx4 v[96:99], v165, s[78:79]
	global_load_dwordx4 v[100:103], v165, s[78:79] offset:16
	s_waitcnt vmcnt(18)
	v_cvt_pk_f32_fp8_e32 v[120:121], v0
	v_cvt_pk_f32_fp8_sdwa v[122:123], v0 src0_sel:WORD_1
	v_cvt_pk_f32_fp8_e32 v[124:125], v1
	v_cvt_pk_f32_fp8_sdwa v[126:127], v1 src0_sel:WORD_1
	v_cvt_pk_f32_fp8_e32 v[128:129], v4
	v_cvt_pk_f32_fp8_sdwa v[130:131], v4 src0_sel:WORD_1
	v_cvt_pk_f32_fp8_e32 v[132:133], v5
	v_cvt_pk_f32_fp8_sdwa v[134:135], v5 src0_sel:WORD_1
	v_pk_mul_f32 v[136:137], v[80:81], v[120:121]
	v_pk_mul_f32 v[138:139], v[80:81], v[128:129]
	v_pk_fma_f32 v[136:137], v[82:83], v[122:123], v[136:137]
	v_pk_fma_f32 v[138:139], v[82:83], v[130:131], v[138:139]
	v_pk_fma_f32 v[136:137], v[84:85], v[124:125], v[136:137]
	v_pk_fma_f32 v[138:139], v[84:85], v[132:133], v[138:139]
	v_pk_fma_f32 v[136:137], v[86:87], v[126:127], v[136:137]
	v_pk_fma_f32 v[138:139], v[86:87], v[134:135], v[138:139]
	v_cvt_pk_f32_fp8_e32 v[120:121], v2
	v_cvt_pk_f32_fp8_sdwa v[122:123], v2 src0_sel:WORD_1
	v_cvt_pk_f32_fp8_e32 v[124:125], v3
	v_cvt_pk_f32_fp8_sdwa v[126:127], v3 src0_sel:WORD_1
	v_cvt_pk_f32_fp8_e32 v[128:129], v6
	v_cvt_pk_f32_fp8_sdwa v[130:131], v6 src0_sel:WORD_1
	v_cvt_pk_f32_fp8_e32 v[132:133], v7
	v_cvt_pk_f32_fp8_sdwa v[134:135], v7 src0_sel:WORD_1
	v_pk_fma_f32 v[136:137], v[88:89], v[120:121], v[136:137]
	v_pk_fma_f32 v[138:139], v[88:89], v[128:129], v[138:139]
	v_pk_fma_f32 v[136:137], v[90:91], v[122:123], v[136:137]
	v_pk_fma_f32 v[138:139], v[90:91], v[130:131], v[138:139]
	v_pk_fma_f32 v[136:137], v[92:93], v[124:125], v[136:137]
	v_pk_fma_f32 v[138:139], v[92:93], v[132:133], v[138:139]
	v_pk_fma_f32 v[136:137], v[94:95], v[126:127], v[136:137]
	v_pk_fma_f32 v[138:139], v[94:95], v[134:135], v[138:139]
	v_add_f32_e32 v104, v136, v137
	v_add_f32_e32 v105, v138, v139
	s_waitcnt lgkmcnt(0)
	v_add_u32_e32 v0, v64, v160
	v_add_u32_e32 v4, v65, v160
	global_load_dwordx4 v[0:3], v0, s[42:43]
	global_load_dwordx4 v[4:7], v4, s[42:43]
	s_waitcnt vmcnt(18)
	v_cvt_pk_f32_fp8_e32 v[120:121], v8
	v_cvt_pk_f32_fp8_sdwa v[122:123], v8 src0_sel:WORD_1
	v_cvt_pk_f32_fp8_e32 v[124:125], v9
	v_cvt_pk_f32_fp8_sdwa v[126:127], v9 src0_sel:WORD_1
	v_cvt_pk_f32_fp8_e32 v[128:129], v12
	v_cvt_pk_f32_fp8_sdwa v[130:131], v12 src0_sel:WORD_1
	v_cvt_pk_f32_fp8_e32 v[132:133], v13
	v_cvt_pk_f32_fp8_sdwa v[134:135], v13 src0_sel:WORD_1
	v_pk_mul_f32 v[136:137], v[80:81], v[120:121]
	v_pk_mul_f32 v[138:139], v[80:81], v[128:129]
	v_pk_fma_f32 v[136:137], v[82:83], v[122:123], v[136:137]
	v_pk_fma_f32 v[138:139], v[82:83], v[130:131], v[138:139]
	v_pk_fma_f32 v[136:137], v[84:85], v[124:125], v[136:137]
	v_pk_fma_f32 v[138:139], v[84:85], v[132:133], v[138:139]
	v_pk_fma_f32 v[136:137], v[86:87], v[126:127], v[136:137]
	v_pk_fma_f32 v[138:139], v[86:87], v[134:135], v[138:139]
	v_cvt_pk_f32_fp8_e32 v[120:121], v10
	v_cvt_pk_f32_fp8_sdwa v[122:123], v10 src0_sel:WORD_1
	v_cvt_pk_f32_fp8_e32 v[124:125], v11
	v_cvt_pk_f32_fp8_sdwa v[126:127], v11 src0_sel:WORD_1
	v_cvt_pk_f32_fp8_e32 v[128:129], v14
	v_cvt_pk_f32_fp8_sdwa v[130:131], v14 src0_sel:WORD_1
	v_cvt_pk_f32_fp8_e32 v[132:133], v15
	v_cvt_pk_f32_fp8_sdwa v[134:135], v15 src0_sel:WORD_1
	v_pk_fma_f32 v[136:137], v[88:89], v[120:121], v[136:137]
	v_pk_fma_f32 v[138:139], v[88:89], v[128:129], v[138:139]
	v_pk_fma_f32 v[136:137], v[90:91], v[122:123], v[136:137]
	v_pk_fma_f32 v[138:139], v[90:91], v[130:131], v[138:139]
	v_pk_fma_f32 v[136:137], v[92:93], v[124:125], v[136:137]
	v_pk_fma_f32 v[138:139], v[92:93], v[132:133], v[138:139]
	v_pk_fma_f32 v[136:137], v[94:95], v[126:127], v[136:137]
	v_pk_fma_f32 v[138:139], v[94:95], v[134:135], v[138:139]
	v_add_f32_e32 v106, v136, v137
	v_add_f32_e32 v107, v138, v139
	v_add_u32_e32 v8, v66, v160
	v_add_u32_e32 v12, v67, v160
	global_load_dwordx4 v[8:11], v8, s[42:43]
	global_load_dwordx4 v[12:15], v12, s[42:43]
	s_waitcnt vmcnt(18)
	v_cvt_pk_f32_fp8_e32 v[120:121], v16
	v_cvt_pk_f32_fp8_sdwa v[122:123], v16 src0_sel:WORD_1
	v_cvt_pk_f32_fp8_e32 v[124:125], v17
	v_cvt_pk_f32_fp8_sdwa v[126:127], v17 src0_sel:WORD_1
	v_cvt_pk_f32_fp8_e32 v[128:129], v20
	v_cvt_pk_f32_fp8_sdwa v[130:131], v20 src0_sel:WORD_1
	v_cvt_pk_f32_fp8_e32 v[132:133], v21
	v_cvt_pk_f32_fp8_sdwa v[134:135], v21 src0_sel:WORD_1
	v_pk_mul_f32 v[136:137], v[80:81], v[120:121]
	v_pk_mul_f32 v[138:139], v[80:81], v[128:129]
	v_pk_fma_f32 v[136:137], v[82:83], v[122:123], v[136:137]
	v_pk_fma_f32 v[138:139], v[82:83], v[130:131], v[138:139]
	v_pk_fma_f32 v[136:137], v[84:85], v[124:125], v[136:137]
	v_pk_fma_f32 v[138:139], v[84:85], v[132:133], v[138:139]
	v_pk_fma_f32 v[136:137], v[86:87], v[126:127], v[136:137]
	v_pk_fma_f32 v[138:139], v[86:87], v[134:135], v[138:139]
	v_cvt_pk_f32_fp8_e32 v[120:121], v18
	v_cvt_pk_f32_fp8_sdwa v[122:123], v18 src0_sel:WORD_1
	v_cvt_pk_f32_fp8_e32 v[124:125], v19
	v_cvt_pk_f32_fp8_sdwa v[126:127], v19 src0_sel:WORD_1
	v_cvt_pk_f32_fp8_e32 v[128:129], v22
	v_cvt_pk_f32_fp8_sdwa v[130:131], v22 src0_sel:WORD_1
	v_cvt_pk_f32_fp8_e32 v[132:133], v23
	v_cvt_pk_f32_fp8_sdwa v[134:135], v23 src0_sel:WORD_1
	v_pk_fma_f32 v[136:137], v[88:89], v[120:121], v[136:137]
	v_pk_fma_f32 v[138:139], v[88:89], v[128:129], v[138:139]
	v_pk_fma_f32 v[136:137], v[90:91], v[122:123], v[136:137]
	v_pk_fma_f32 v[138:139], v[90:91], v[130:131], v[138:139]
	v_pk_fma_f32 v[136:137], v[92:93], v[124:125], v[136:137]
	v_pk_fma_f32 v[138:139], v[92:93], v[132:133], v[138:139]
	v_pk_fma_f32 v[136:137], v[94:95], v[126:127], v[136:137]
	v_pk_fma_f32 v[138:139], v[94:95], v[134:135], v[138:139]
	v_add_f32_e32 v108, v136, v137
	v_add_f32_e32 v109, v138, v139
	v_add_u32_e32 v16, v68, v160
	v_add_u32_e32 v20, v69, v160
	global_load_dwordx4 v[16:19], v16, s[42:43]
	global_load_dwordx4 v[20:23], v20, s[42:43]
	s_waitcnt vmcnt(18)
	v_cvt_pk_f32_fp8_e32 v[120:121], v24
	v_cvt_pk_f32_fp8_sdwa v[122:123], v24 src0_sel:WORD_1
	v_cvt_pk_f32_fp8_e32 v[124:125], v25
	v_cvt_pk_f32_fp8_sdwa v[126:127], v25 src0_sel:WORD_1
	v_cvt_pk_f32_fp8_e32 v[128:129], v28
	v_cvt_pk_f32_fp8_sdwa v[130:131], v28 src0_sel:WORD_1
	v_cvt_pk_f32_fp8_e32 v[132:133], v29
	v_cvt_pk_f32_fp8_sdwa v[134:135], v29 src0_sel:WORD_1
	v_pk_mul_f32 v[136:137], v[80:81], v[120:121]
	v_pk_mul_f32 v[138:139], v[80:81], v[128:129]
	v_pk_fma_f32 v[136:137], v[82:83], v[122:123], v[136:137]
	v_pk_fma_f32 v[138:139], v[82:83], v[130:131], v[138:139]
	v_pk_fma_f32 v[136:137], v[84:85], v[124:125], v[136:137]
	v_pk_fma_f32 v[138:139], v[84:85], v[132:133], v[138:139]
	v_pk_fma_f32 v[136:137], v[86:87], v[126:127], v[136:137]
	v_pk_fma_f32 v[138:139], v[86:87], v[134:135], v[138:139]
	v_cvt_pk_f32_fp8_e32 v[120:121], v26
	v_cvt_pk_f32_fp8_sdwa v[122:123], v26 src0_sel:WORD_1
	v_cvt_pk_f32_fp8_e32 v[124:125], v27
	v_cvt_pk_f32_fp8_sdwa v[126:127], v27 src0_sel:WORD_1
	v_cvt_pk_f32_fp8_e32 v[128:129], v30
	v_cvt_pk_f32_fp8_sdwa v[130:131], v30 src0_sel:WORD_1
	v_cvt_pk_f32_fp8_e32 v[132:133], v31
	v_cvt_pk_f32_fp8_sdwa v[134:135], v31 src0_sel:WORD_1
	v_pk_fma_f32 v[136:137], v[88:89], v[120:121], v[136:137]
	v_pk_fma_f32 v[138:139], v[88:89], v[128:129], v[138:139]
	v_pk_fma_f32 v[136:137], v[90:91], v[122:123], v[136:137]
	v_pk_fma_f32 v[138:139], v[90:91], v[130:131], v[138:139]
	v_pk_fma_f32 v[136:137], v[92:93], v[124:125], v[136:137]
	v_pk_fma_f32 v[138:139], v[92:93], v[132:133], v[138:139]
	v_pk_fma_f32 v[136:137], v[94:95], v[126:127], v[136:137]
	v_pk_fma_f32 v[138:139], v[94:95], v[134:135], v[138:139]
	v_add_f32_e32 v110, v136, v137
	v_add_f32_e32 v111, v138, v139
	v_add_u32_e32 v24, v70, v160
	v_add_u32_e32 v28, v71, v160
	global_load_dwordx4 v[24:27], v24, s[42:43]
	global_load_dwordx4 v[28:31], v28, s[42:43]
	s_waitcnt vmcnt(18)
	v_cvt_pk_f32_fp8_e32 v[120:121], v32
	v_cvt_pk_f32_fp8_sdwa v[122:123], v32 src0_sel:WORD_1
	v_cvt_pk_f32_fp8_e32 v[124:125], v33
	v_cvt_pk_f32_fp8_sdwa v[126:127], v33 src0_sel:WORD_1
	v_cvt_pk_f32_fp8_e32 v[128:129], v36
	v_cvt_pk_f32_fp8_sdwa v[130:131], v36 src0_sel:WORD_1
	v_cvt_pk_f32_fp8_e32 v[132:133], v37
	v_cvt_pk_f32_fp8_sdwa v[134:135], v37 src0_sel:WORD_1
	v_pk_mul_f32 v[136:137], v[80:81], v[120:121]
	v_pk_mul_f32 v[138:139], v[80:81], v[128:129]
	v_pk_fma_f32 v[136:137], v[82:83], v[122:123], v[136:137]
	v_pk_fma_f32 v[138:139], v[82:83], v[130:131], v[138:139]
	v_pk_fma_f32 v[136:137], v[84:85], v[124:125], v[136:137]
	v_pk_fma_f32 v[138:139], v[84:85], v[132:133], v[138:139]
	v_pk_fma_f32 v[136:137], v[86:87], v[126:127], v[136:137]
	v_pk_fma_f32 v[138:139], v[86:87], v[134:135], v[138:139]
	v_cvt_pk_f32_fp8_e32 v[120:121], v34
	v_cvt_pk_f32_fp8_sdwa v[122:123], v34 src0_sel:WORD_1
	v_cvt_pk_f32_fp8_e32 v[124:125], v35
	v_cvt_pk_f32_fp8_sdwa v[126:127], v35 src0_sel:WORD_1
	v_cvt_pk_f32_fp8_e32 v[128:129], v38
	v_cvt_pk_f32_fp8_sdwa v[130:131], v38 src0_sel:WORD_1
	v_cvt_pk_f32_fp8_e32 v[132:133], v39
	v_cvt_pk_f32_fp8_sdwa v[134:135], v39 src0_sel:WORD_1
	v_pk_fma_f32 v[136:137], v[88:89], v[120:121], v[136:137]
	v_pk_fma_f32 v[138:139], v[88:89], v[128:129], v[138:139]
	v_pk_fma_f32 v[136:137], v[90:91], v[122:123], v[136:137]
	v_pk_fma_f32 v[138:139], v[90:91], v[130:131], v[138:139]
	v_pk_fma_f32 v[136:137], v[92:93], v[124:125], v[136:137]
	v_pk_fma_f32 v[138:139], v[92:93], v[132:133], v[138:139]
	v_pk_fma_f32 v[136:137], v[94:95], v[126:127], v[136:137]
	v_pk_fma_f32 v[138:139], v[94:95], v[134:135], v[138:139]
	v_add_f32_e32 v112, v136, v137
	v_add_f32_e32 v113, v138, v139
	v_add_u32_e32 v32, v72, v160
	v_add_u32_e32 v36, v73, v160
	global_load_dwordx4 v[32:35], v32, s[42:43]
	global_load_dwordx4 v[36:39], v36, s[42:43]
	s_waitcnt vmcnt(18)
	v_cvt_pk_f32_fp8_e32 v[120:121], v40
	v_cvt_pk_f32_fp8_sdwa v[122:123], v40 src0_sel:WORD_1
	v_cvt_pk_f32_fp8_e32 v[124:125], v41
	v_cvt_pk_f32_fp8_sdwa v[126:127], v41 src0_sel:WORD_1
	v_cvt_pk_f32_fp8_e32 v[128:129], v44
	v_cvt_pk_f32_fp8_sdwa v[130:131], v44 src0_sel:WORD_1
	v_cvt_pk_f32_fp8_e32 v[132:133], v45
	v_cvt_pk_f32_fp8_sdwa v[134:135], v45 src0_sel:WORD_1
	v_pk_mul_f32 v[136:137], v[80:81], v[120:121]
	v_pk_mul_f32 v[138:139], v[80:81], v[128:129]
	v_pk_fma_f32 v[136:137], v[82:83], v[122:123], v[136:137]
	v_pk_fma_f32 v[138:139], v[82:83], v[130:131], v[138:139]
	v_pk_fma_f32 v[136:137], v[84:85], v[124:125], v[136:137]
	v_pk_fma_f32 v[138:139], v[84:85], v[132:133], v[138:139]
	v_pk_fma_f32 v[136:137], v[86:87], v[126:127], v[136:137]
	v_pk_fma_f32 v[138:139], v[86:87], v[134:135], v[138:139]
	v_cvt_pk_f32_fp8_e32 v[120:121], v42
	v_cvt_pk_f32_fp8_sdwa v[122:123], v42 src0_sel:WORD_1
	v_cvt_pk_f32_fp8_e32 v[124:125], v43
	v_cvt_pk_f32_fp8_sdwa v[126:127], v43 src0_sel:WORD_1
	v_cvt_pk_f32_fp8_e32 v[128:129], v46
	v_cvt_pk_f32_fp8_sdwa v[130:131], v46 src0_sel:WORD_1
	v_cvt_pk_f32_fp8_e32 v[132:133], v47
	v_cvt_pk_f32_fp8_sdwa v[134:135], v47 src0_sel:WORD_1
	v_pk_fma_f32 v[136:137], v[88:89], v[120:121], v[136:137]
	v_pk_fma_f32 v[138:139], v[88:89], v[128:129], v[138:139]
	v_pk_fma_f32 v[136:137], v[90:91], v[122:123], v[136:137]
	v_pk_fma_f32 v[138:139], v[90:91], v[130:131], v[138:139]
	v_pk_fma_f32 v[136:137], v[92:93], v[124:125], v[136:137]
	v_pk_fma_f32 v[138:139], v[92:93], v[132:133], v[138:139]
	v_pk_fma_f32 v[136:137], v[94:95], v[126:127], v[136:137]
	v_pk_fma_f32 v[138:139], v[94:95], v[134:135], v[138:139]
	v_add_f32_e32 v114, v136, v137
	v_add_f32_e32 v115, v138, v139
	v_add_u32_e32 v40, v74, v160
	v_add_u32_e32 v44, v75, v160
	global_load_dwordx4 v[40:43], v40, s[42:43]
	global_load_dwordx4 v[44:47], v44, s[42:43]
	s_waitcnt vmcnt(18)
	v_cvt_pk_f32_fp8_e32 v[120:121], v48
	v_cvt_pk_f32_fp8_sdwa v[122:123], v48 src0_sel:WORD_1
	v_cvt_pk_f32_fp8_e32 v[124:125], v49
	v_cvt_pk_f32_fp8_sdwa v[126:127], v49 src0_sel:WORD_1
	v_cvt_pk_f32_fp8_e32 v[128:129], v52
	v_cvt_pk_f32_fp8_sdwa v[130:131], v52 src0_sel:WORD_1
	v_cvt_pk_f32_fp8_e32 v[132:133], v53
	v_cvt_pk_f32_fp8_sdwa v[134:135], v53 src0_sel:WORD_1
	v_pk_mul_f32 v[136:137], v[80:81], v[120:121]
	v_pk_mul_f32 v[138:139], v[80:81], v[128:129]
	v_pk_fma_f32 v[136:137], v[82:83], v[122:123], v[136:137]
	v_pk_fma_f32 v[138:139], v[82:83], v[130:131], v[138:139]
	v_pk_fma_f32 v[136:137], v[84:85], v[124:125], v[136:137]
	v_pk_fma_f32 v[138:139], v[84:85], v[132:133], v[138:139]
	v_pk_fma_f32 v[136:137], v[86:87], v[126:127], v[136:137]
	v_pk_fma_f32 v[138:139], v[86:87], v[134:135], v[138:139]
	v_cvt_pk_f32_fp8_e32 v[120:121], v50
	v_cvt_pk_f32_fp8_sdwa v[122:123], v50 src0_sel:WORD_1
	v_cvt_pk_f32_fp8_e32 v[124:125], v51
	v_cvt_pk_f32_fp8_sdwa v[126:127], v51 src0_sel:WORD_1
	v_cvt_pk_f32_fp8_e32 v[128:129], v54
	v_cvt_pk_f32_fp8_sdwa v[130:131], v54 src0_sel:WORD_1
	v_cvt_pk_f32_fp8_e32 v[132:133], v55
	v_cvt_pk_f32_fp8_sdwa v[134:135], v55 src0_sel:WORD_1
	v_pk_fma_f32 v[136:137], v[88:89], v[120:121], v[136:137]
	v_pk_fma_f32 v[138:139], v[88:89], v[128:129], v[138:139]
	v_pk_fma_f32 v[136:137], v[90:91], v[122:123], v[136:137]
	v_pk_fma_f32 v[138:139], v[90:91], v[130:131], v[138:139]
	v_pk_fma_f32 v[136:137], v[92:93], v[124:125], v[136:137]
	v_pk_fma_f32 v[138:139], v[92:93], v[132:133], v[138:139]
	v_pk_fma_f32 v[136:137], v[94:95], v[126:127], v[136:137]
	v_pk_fma_f32 v[138:139], v[94:95], v[134:135], v[138:139]
	v_add_f32_e32 v116, v136, v137
	v_add_f32_e32 v117, v138, v139
	v_add_u32_e32 v48, v76, v160
	v_add_u32_e32 v52, v77, v160
	global_load_dwordx4 v[48:51], v48, s[42:43]
	global_load_dwordx4 v[52:55], v52, s[42:43]
	s_waitcnt vmcnt(18)
; DI void phase_peer(const Params& p, int l, int bid, int nblk) {
;     ...
;     PEER_LOAD(0, 0, UB)
; #pragma unroll 1
;     for (int k = 0; k < 16; k += 2) {
;       PEER_LOAD(1, k + 1, UB)
;       __builtin_amdgcn_sched_barrier(0);
;       PEER_DOT(0, k)
;       { const int kn = (k + 2 < 16) ? k + 2 : 15; PEER_LOAD(0, kn, UB) }
;       __builtin_amdgcn_sched_barrier(0);
;       PEER_DOT(1, k + 1)
;     }
;     const float ga0 = gelu_tanh(act0 * (1.f / U_SCALE)) * g0 * (1.f / V_SCALE);
;     const float ga1 = gelu_tanh(act1 * (1.f / U_SCALE)) * g1 * (1.f / V_SCALE);
	v_cvt_pk_f32_fp8_e32 v[120:121], v56
	v_cvt_pk_f32_fp8_sdwa v[122:123], v56 src0_sel:WORD_1
	v_cvt_pk_f32_fp8_e32 v[124:125], v57
	v_cvt_pk_f32_fp8_sdwa v[126:127], v57 src0_sel:WORD_1
	v_cvt_pk_f32_fp8_e32 v[128:129], v60
	v_cvt_pk_f32_fp8_sdwa v[130:131], v60 src0_sel:WORD_1
	v_cvt_pk_f32_fp8_e32 v[132:133], v61
	v_cvt_pk_f32_fp8_sdwa v[134:135], v61 src0_sel:WORD_1
	v_pk_mul_f32 v[136:137], v[80:81], v[120:121]
	v_pk_mul_f32 v[138:139], v[80:81], v[128:129]
	v_pk_fma_f32 v[136:137], v[82:83], v[122:123], v[136:137]
	v_pk_fma_f32 v[138:139], v[82:83], v[130:131], v[138:139]
	v_pk_fma_f32 v[136:137], v[84:85], v[124:125], v[136:137]
	v_pk_fma_f32 v[138:139], v[84:85], v[132:133], v[138:139]
	v_pk_fma_f32 v[136:137], v[86:87], v[126:127], v[136:137]
	v_pk_fma_f32 v[138:139], v[86:87], v[134:135], v[138:139]
	v_cvt_pk_f32_fp8_e32 v[120:121], v58
	v_cvt_pk_f32_fp8_sdwa v[122:123], v58 src0_sel:WORD_1
	v_cvt_pk_f32_fp8_e32 v[124:125], v59
	v_cvt_pk_f32_fp8_sdwa v[126:127], v59 src0_sel:WORD_1
	v_cvt_pk_f32_fp8_e32 v[128:129], v62
	v_cvt_pk_f32_fp8_sdwa v[130:131], v62 src0_sel:WORD_1
	v_cvt_pk_f32_fp8_e32 v[132:133], v63
	v_cvt_pk_f32_fp8_sdwa v[134:135], v63 src0_sel:WORD_1
	v_pk_fma_f32 v[136:137], v[88:89], v[120:121], v[136:137]
	v_pk_fma_f32 v[138:139], v[88:89], v[128:129], v[138:139]
	v_pk_fma_f32 v[136:137], v[90:91], v[122:123], v[136:137]
	v_pk_fma_f32 v[138:139], v[90:91], v[130:131], v[138:139]
	v_pk_fma_f32 v[136:137], v[92:93], v[124:125], v[136:137]
	v_pk_fma_f32 v[138:139], v[92:93], v[132:133], v[138:139]
	v_pk_fma_f32 v[136:137], v[94:95], v[126:127], v[136:137]
	v_pk_fma_f32 v[138:139], v[94:95], v[134:135], v[138:139]
	v_add_f32_e32 v118, v136, v137
	v_add_f32_e32 v119, v138, v139
	v_add_u32_e32 v56, v78, v160
	v_add_u32_e32 v60, v79, v160
	global_load_dwordx4 v[56:59], v56, s[42:43]
	global_load_dwordx4 v[60:63], v60, s[42:43]
	v_cndmask_b32_e64 v120, v104, v105, s[34:35]
	v_cndmask_b32_e64 v128, v105, v104, s[34:35]
	v_cndmask_b32_e64 v121, v106, v107, s[34:35]
	v_cndmask_b32_e64 v129, v107, v106, s[34:35]
	v_cndmask_b32_e64 v122, v108, v109, s[34:35]
	v_cndmask_b32_e64 v130, v109, v108, s[34:35]
	v_cndmask_b32_e64 v123, v110, v111, s[34:35]
	v_cndmask_b32_e64 v131, v111, v110, s[34:35]
	v_cndmask_b32_e64 v124, v112, v113, s[34:35]
	v_cndmask_b32_e64 v132, v113, v112, s[34:35]
	v_cndmask_b32_e64 v125, v114, v115, s[34:35]
	v_cndmask_b32_e64 v133, v115, v114, s[34:35]
	v_cndmask_b32_e64 v126, v116, v117, s[34:35]
	v_cndmask_b32_e64 v134, v117, v116, s[34:35]
	v_cndmask_b32_e64 v127, v118, v119, s[34:35]
	v_cndmask_b32_e64 v135, v119, v118, s[34:35]
	v_add_f32_dpp v104, v128, v120 row_half_mirror row_mask:0xf bank_mask:0xf
	v_add_f32_dpp v105, v129, v121 row_half_mirror row_mask:0xf bank_mask:0xf
	v_add_f32_dpp v106, v130, v122 row_half_mirror row_mask:0xf bank_mask:0xf
	v_add_f32_dpp v107, v131, v123 row_half_mirror row_mask:0xf bank_mask:0xf
	v_add_f32_dpp v108, v132, v124 row_half_mirror row_mask:0xf bank_mask:0xf
	v_add_f32_dpp v109, v133, v125 row_half_mirror row_mask:0xf bank_mask:0xf
	v_add_f32_dpp v110, v134, v126 row_half_mirror row_mask:0xf bank_mask:0xf
	v_add_f32_dpp v111, v135, v127 row_half_mirror row_mask:0xf bank_mask:0xf
	s_nop 0
	v_cndmask_b32_e64 v120, v104, v105, s[36:37]
	v_cndmask_b32_e64 v128, v105, v104, s[36:37]
	v_cndmask_b32_e64 v121, v106, v107, s[36:37]
	v_cndmask_b32_e64 v129, v107, v106, s[36:37]
	v_cndmask_b32_e64 v122, v108, v109, s[36:37]
	v_cndmask_b32_e64 v130, v109, v108, s[36:37]
	v_cndmask_b32_e64 v123, v110, v111, s[36:37]
	v_cndmask_b32_e64 v131, v111, v110, s[36:37]
	v_add_f32_dpp v104, v128, v120 quad_perm:[1,0,3,2] row_mask:0xf bank_mask:0xf
	v_add_f32_dpp v105, v129, v121 quad_perm:[1,0,3,2] row_mask:0xf bank_mask:0xf
	v_add_f32_dpp v106, v130, v122 quad_perm:[1,0,3,2] row_mask:0xf bank_mask:0xf
	v_add_f32_dpp v107, v131, v123 quad_perm:[1,0,3,2] row_mask:0xf bank_mask:0xf
	s_nop 0
	v_cndmask_b32_e64 v120, v104, v105, s[38:39]
	v_cndmask_b32_e64 v128, v105, v104, s[38:39]
	v_cndmask_b32_e64 v121, v106, v107, s[38:39]
	v_cndmask_b32_e64 v129, v107, v106, s[38:39]
	s_nop 0
	v_add_f32_dpp v104, v128, v120 quad_perm:[2,3,0,1] row_mask:0xf bank_mask:0xf
	v_add_f32_dpp v105, v129, v121 quad_perm:[2,3,0,1] row_mask:0xf bank_mask:0xf
	s_nop 0
	v_add_f32_e32 v104, v104, v140
	v_add_f32_e32 v105, v105, v141
	s_cmp_eq_u32 s46, 7
	s_cbranch_scc0 .Lpeer_u_store
	s_waitcnt vmcnt(18)
	v_mul_f32_e32 v146, 0x3c800000, v104
	v_mul_f32_e32 v147, v146, v146
	v_fmaak_f32 v147, v147, v168, 0x3fcc422a
	v_mul_f32_e32 v147, v146, v147
	v_mul_f32_e32 v147, 0xbfb8aa3b, v147
	v_exp_f32_e32 v147, v147
	s_nop 0
	v_add_f32_e32 v147, 1.0, v147
	v_rcp_f32_e32 v147, v147
	v_mul_f32_e32 v146, v146, v142
	v_mul_f32_e32 v104, v146, v147
	v_mul_f32_e32 v149, 0x3c800000, v105
	v_mul_f32_e32 v150, v149, v149
	v_fmaak_f32 v150, v150, v168, 0x3fcc422a
	v_mul_f32_e32 v150, v149, v150
	v_mul_f32_e32 v150, 0xbfb8aa3b, v150
	v_exp_f32_e32 v150, v150
	s_nop 0
	v_add_f32_e32 v150, 1.0, v150
	v_rcp_f32_e32 v150, v150
	v_mul_f32_e32 v149, v149, v143
	v_mul_f32_e32 v105, v149, v150
.Lpeer_u_store:
	ds_write2_b32 v145, v104, v105 offset1:8
	s_mov_b32 s46, s62
	s_mov_b32 s47, s63
	s_mov_b32 s48, s64
	s_mov_b32 s50, s65
	s_add_i32 s49, s49, -1
	s_cmp_lg_u32 s49, 0
	s_cbranch_scc1 .Lpeer_u_top
	s_waitcnt vmcnt(0) lgkmcnt(0)
	s_add_u32 s44, s96, 0xfa00000
	s_addc_u32 s45, s97, 0
	s_mov_b32 s42, s44
	s_mov_b32 s43, s45
	s_mov_b32 s46, 0
	s_mov_b32 s47, 0
	s_mov_b32 s50, 0
	s_lshl_b32 s49, s75, 3
	s_cmp_ge_u32 s47, s55
	s_addc_u32 s48, s47, 0
	s_cmp_ge_u32 s48, s66
	s_addc_u32 s48, s48, 0
	s_lshl_b32 s48, s48, 11
	s_add_i32 s48, s48, s67
	v_add_u32_e32 v144, s50, v162
	ds_read_b128 v[64:67], v144
	ds_read_b128 v[68:71], v144 offset:16
	ds_read_b128 v[72:75], v144 offset:32
	ds_read_b128 v[76:79], v144 offset:48
	s_waitcnt lgkmcnt(0)
	v_add_u32_e32 v0, v64, v160
	v_add_u32_e32 v4, v65, v160
	global_load_dwordx4 v[0:3], v0, s[42:43]
	global_load_dwordx4 v[4:7], v4, s[42:43]
	v_add_u32_e32 v8, v66, v160
	v_add_u32_e32 v12, v67, v160
	global_load_dwordx4 v[8:11], v8, s[42:43]
	global_load_dwordx4 v[12:15], v12, s[42:43]
	v_add_u32_e32 v16, v68, v160
	v_add_u32_e32 v20, v69, v160
	global_load_dwordx4 v[16:19], v16, s[42:43]
	global_load_dwordx4 v[20:23], v20, s[42:43]
	v_add_u32_e32 v24, v70, v160
	v_add_u32_e32 v28, v71, v160
	global_load_dwordx4 v[24:27], v24, s[42:43]
	global_load_dwordx4 v[28:31], v28, s[42:43]
	v_add_u32_e32 v32, v72, v160
	v_add_u32_e32 v36, v73, v160
	global_load_dwordx4 v[32:35], v32, s[42:43]
	global_load_dwordx4 v[36:39], v36, s[42:43]
	v_add_u32_e32 v40, v74, v160
	v_add_u32_e32 v44, v75, v160
	global_load_dwordx4 v[40:43], v40, s[42:43]
	global_load_dwordx4 v[44:47], v44, s[42:43]
	v_add_u32_e32 v48, v76, v160
	v_add_u32_e32 v52, v77, v160
	global_load_dwordx4 v[48:51], v48, s[42:43]
	global_load_dwordx4 v[52:55], v52, s[42:43]
	v_add_u32_e32 v56, v78, v160
	v_add_u32_e32 v60, v79, v160
	global_load_dwordx4 v[56:59], v56, s[42:43]
	global_load_dwordx4 v[60:63], v60, s[42:43]

; DI void phase_peer(const Params& p, int l, int bid, int nblk) {
;     ...
; #pragma unroll
;     for (int i = 0; i < 16; ++i) acc[i] = 0.f;
;     ...
;     PEER_LOAD(0, 0, VB)
; #pragma unroll 1
;     for (int k = 0; k < 16; k += 2) {
;       PEER_LOAD(1, k + 1, VB)
;       __builtin_amdgcn_sched_barrier(0);
;       PEER_ACC(0, k)
;       { const int kn = (k + 2 < 16) ? k + 2 : 15; PEER_LOAD(0, kn, VB) }
;       __builtin_amdgcn_sched_barrier(0);
;       PEER_ACC(1, k + 1)
;     }
.Lpeer_v_ptr:
	s_cmp_lg_u64 s[70:71], 0
	s_cselect_b32 s86, 17, 0
	s_add_i32 s84, s84, s86
	s_mul_i32 s84, s84, 0x6000
	s_add_u32 s82, s96, 0x1be09000
	s_addc_u32 s83, s97, 0
	s_add_u32 s82, s82, s84
	s_addc_u32 s83, s83, 0
	s_lshl_b32 s86, s46, 9
	s_add_u32 s80, s80, s86
	s_addc_u32 s81, s81, 0
	s_add_u32 s82, s82, s86
	s_addc_u32 s83, s83, 0
	v_add_u32_e32 v144, s65, v162
	ds_read_b128 v[64:67], v144
	ds_read_b128 v[68:71], v144 offset:16
	ds_read_b128 v[72:75], v144 offset:32
	ds_read_b128 v[76:79], v144 offset:48
	v_add_u32_e32 v145, s50, v164
	ds_read_b128 v[80:83], v145
	ds_read_b128 v[84:87], v145 offset:16
	ds_read_b128 v[88:91], v145 offset:32
	ds_read_b128 v[92:95], v145 offset:48
	v_mov_b64_e32 v[96:97], 0
	v_mov_b64_e32 v[98:99], 0
	v_mov_b64_e32 v[100:101], 0
	v_mov_b64_e32 v[102:103], 0
	v_mov_b64_e32 v[104:105], 0
	v_mov_b64_e32 v[106:107], 0
	v_mov_b64_e32 v[108:109], 0
	v_mov_b64_e32 v[110:111], 0
	global_load_dwordx2 v[140:141], v166, s[80:81]
	global_load_dwordx2 v[142:143], v166, s[82:83]
	s_waitcnt lgkmcnt(0)
	s_waitcnt vmcnt(16)
	v_cvt_pk_f32_fp8_e32 v[120:121], v0
	v_cvt_pk_f32_fp8_sdwa v[122:123], v0 src0_sel:WORD_1
	v_cvt_pk_f32_fp8_e32 v[124:125], v1
	v_cvt_pk_f32_fp8_sdwa v[126:127], v1 src0_sel:WORD_1
	v_pk_fma_f32 v[96:97], v[120:121], v[80:81], v[96:97] op_sel_hi:[1,0,1]
	v_pk_fma_f32 v[98:99], v[122:123], v[80:81], v[98:99] op_sel_hi:[1,0,1]
	v_pk_fma_f32 v[100:101], v[124:125], v[80:81], v[100:101] op_sel_hi:[1,0,1]
	v_pk_fma_f32 v[102:103], v[126:127], v[80:81], v[102:103] op_sel_hi:[1,0,1]
	v_cvt_pk_f32_fp8_e32 v[120:121], v2
	v_cvt_pk_f32_fp8_sdwa v[122:123], v2 src0_sel:WORD_1
	v_cvt_pk_f32_fp8_e32 v[124:125], v3
	v_cvt_pk_f32_fp8_sdwa v[126:127], v3 src0_sel:WORD_1
	v_pk_fma_f32 v[104:105], v[120:121], v[80:81], v[104:105] op_sel_hi:[1,0,1]
	v_pk_fma_f32 v[106:107], v[122:123], v[80:81], v[106:107] op_sel_hi:[1,0,1]
	v_pk_fma_f32 v[108:109], v[124:125], v[80:81], v[108:109] op_sel_hi:[1,0,1]
	v_pk_fma_f32 v[110:111], v[126:127], v[80:81], v[110:111] op_sel_hi:[1,0,1]
	v_cvt_pk_f32_fp8_e32 v[128:129], v4
	v_cvt_pk_f32_fp8_sdwa v[130:131], v4 src0_sel:WORD_1
	v_cvt_pk_f32_fp8_e32 v[132:133], v5
	v_cvt_pk_f32_fp8_sdwa v[134:135], v5 src0_sel:WORD_1
	v_pk_fma_f32 v[96:97], v[128:129], v[80:81], v[96:97] op_sel:[0,1,0]
	v_pk_fma_f32 v[98:99], v[130:131], v[80:81], v[98:99] op_sel:[0,1,0]
	v_pk_fma_f32 v[100:101], v[132:133], v[80:81], v[100:101] op_sel:[0,1,0]
	v_pk_fma_f32 v[102:103], v[134:135], v[80:81], v[102:103] op_sel:[0,1,0]
	v_cvt_pk_f32_fp8_e32 v[128:129], v6
	v_cvt_pk_f32_fp8_sdwa v[130:131], v6 src0_sel:WORD_1
	v_cvt_pk_f32_fp8_e32 v[132:133], v7
	v_cvt_pk_f32_fp8_sdwa v[134:135], v7 src0_sel:WORD_1
	v_pk_fma_f32 v[104:105], v[128:129], v[80:81], v[104:105] op_sel:[0,1,0]
	v_pk_fma_f32 v[106:107], v[130:131], v[80:81], v[106:107] op_sel:[0,1,0]
	v_pk_fma_f32 v[108:109], v[132:133], v[80:81], v[108:109] op_sel:[0,1,0]
	v_pk_fma_f32 v[110:111], v[134:135], v[80:81], v[110:111] op_sel:[0,1,0]
	v_add_u32_e32 v0, v64, v160
	v_add_u32_e32 v4, v65, v160
	global_load_dwordx4 v[0:3], v0, s[42:43]
	global_load_dwordx4 v[4:7], v4, s[42:43]
	s_waitcnt vmcnt(16)
	v_cvt_pk_f32_fp8_e32 v[120:121], v8
	v_cvt_pk_f32_fp8_sdwa v[122:123], v8 src0_sel:WORD_1
	v_cvt_pk_f32_fp8_e32 v[124:125], v9
	v_cvt_pk_f32_fp8_sdwa v[126:127], v9 src0_sel:WORD_1
	v_pk_fma_f32 v[96:97], v[120:121], v[82:83], v[96:97] op_sel_hi:[1,0,1]
	v_pk_fma_f32 v[98:99], v[122:123], v[82:83], v[98:99] op_sel_hi:[1,0,1]
	v_pk_fma_f32 v[100:101], v[124:125], v[82:83], v[100:101] op_sel_hi:[1,0,1]
	v_pk_fma_f32 v[102:103], v[126:127], v[82:83], v[102:103] op_sel_hi:[1,0,1]
	v_cvt_pk_f32_fp8_e32 v[120:121], v10
	v_cvt_pk_f32_fp8_sdwa v[122:123], v10 src0_sel:WORD_1
	v_cvt_pk_f32_fp8_e32 v[124:125], v11
	v_cvt_pk_f32_fp8_sdwa v[126:127], v11 src0_sel:WORD_1
	v_pk_fma_f32 v[104:105], v[120:121], v[82:83], v[104:105] op_sel_hi:[1,0,1]
	v_pk_fma_f32 v[106:107], v[122:123], v[82:83], v[106:107] op_sel_hi:[1,0,1]
	v_pk_fma_f32 v[108:109], v[124:125], v[82:83], v[108:109] op_sel_hi:[1,0,1]
	v_pk_fma_f32 v[110:111], v[126:127], v[82:83], v[110:111] op_sel_hi:[1,0,1]
	v_cvt_pk_f32_fp8_e32 v[128:129], v12
	v_cvt_pk_f32_fp8_sdwa v[130:131], v12 src0_sel:WORD_1
	v_cvt_pk_f32_fp8_e32 v[132:133], v13
	v_cvt_pk_f32_fp8_sdwa v[134:135], v13 src0_sel:WORD_1
	v_pk_fma_f32 v[96:97], v[128:129], v[82:83], v[96:97] op_sel:[0,1,0]
	v_pk_fma_f32 v[98:99], v[130:131], v[82:83], v[98:99] op_sel:[0,1,0]
	v_pk_fma_f32 v[100:101], v[132:133], v[82:83], v[100:101] op_sel:[0,1,0]
	v_pk_fma_f32 v[102:103], v[134:135], v[82:83], v[102:103] op_sel:[0,1,0]
	v_cvt_pk_f32_fp8_e32 v[128:129], v14
	v_cvt_pk_f32_fp8_sdwa v[130:131], v14 src0_sel:WORD_1
	v_cvt_pk_f32_fp8_e32 v[132:133], v15
	v_cvt_pk_f32_fp8_sdwa v[134:135], v15 src0_sel:WORD_1
	v_pk_fma_f32 v[104:105], v[128:129], v[82:83], v[104:105] op_sel:[0,1,0]
	v_pk_fma_f32 v[106:107], v[130:131], v[82:83], v[106:107] op_sel:[0,1,0]
	v_pk_fma_f32 v[108:109], v[132:133], v[82:83], v[108:109] op_sel:[0,1,0]
	v_pk_fma_f32 v[110:111], v[134:135], v[82:83], v[110:111] op_sel:[0,1,0]
	v_add_u32_e32 v8, v66, v160
	v_add_u32_e32 v12, v67, v160
	global_load_dwordx4 v[8:11], v8, s[42:43]
	global_load_dwordx4 v[12:15], v12, s[42:43]
	s_waitcnt vmcnt(16)
	v_cvt_pk_f32_fp8_e32 v[120:121], v16
	v_cvt_pk_f32_fp8_sdwa v[122:123], v16 src0_sel:WORD_1
	v_cvt_pk_f32_fp8_e32 v[124:125], v17
	v_cvt_pk_f32_fp8_sdwa v[126:127], v17 src0_sel:WORD_1
	v_pk_fma_f32 v[96:97], v[120:121], v[84:85], v[96:97] op_sel_hi:[1,0,1]
	v_pk_fma_f32 v[98:99], v[122:123], v[84:85], v[98:99] op_sel_hi:[1,0,1]
	v_pk_fma_f32 v[100:101], v[124:125], v[84:85], v[100:101] op_sel_hi:[1,0,1]
	v_pk_fma_f32 v[102:103], v[126:127], v[84:85], v[102:103] op_sel_hi:[1,0,1]
	v_cvt_pk_f32_fp8_e32 v[120:121], v18
	v_cvt_pk_f32_fp8_sdwa v[122:123], v18 src0_sel:WORD_1
	v_cvt_pk_f32_fp8_e32 v[124:125], v19
	v_cvt_pk_f32_fp8_sdwa v[126:127], v19 src0_sel:WORD_1
	v_pk_fma_f32 v[104:105], v[120:121], v[84:85], v[104:105] op_sel_hi:[1,0,1]
	v_pk_fma_f32 v[106:107], v[122:123], v[84:85], v[106:107] op_sel_hi:[1,0,1]
	v_pk_fma_f32 v[108:109], v[124:125], v[84:85], v[108:109] op_sel_hi:[1,0,1]
	v_pk_fma_f32 v[110:111], v[126:127], v[84:85], v[110:111] op_sel_hi:[1,0,1]
	v_cvt_pk_f32_fp8_e32 v[128:129], v20
	v_cvt_pk_f32_fp8_sdwa v[130:131], v20 src0_sel:WORD_1
	v_cvt_pk_f32_fp8_e32 v[132:133], v21
	v_cvt_pk_f32_fp8_sdwa v[134:135], v21 src0_sel:WORD_1
	v_pk_fma_f32 v[96:97], v[128:129], v[84:85], v[96:97] op_sel:[0,1,0]
	v_pk_fma_f32 v[98:99], v[130:131], v[84:85], v[98:99] op_sel:[0,1,0]
	v_pk_fma_f32 v[100:101], v[132:133], v[84:85], v[100:101] op_sel:[0,1,0]
	v_pk_fma_f32 v[102:103], v[134:135], v[84:85], v[102:103] op_sel:[0,1,0]
	v_cvt_pk_f32_fp8_e32 v[128:129], v22
	v_cvt_pk_f32_fp8_sdwa v[130:131], v22 src0_sel:WORD_1
	v_cvt_pk_f32_fp8_e32 v[132:133], v23
	v_cvt_pk_f32_fp8_sdwa v[134:135], v23 src0_sel:WORD_1
	v_pk_fma_f32 v[104:105], v[128:129], v[84:85], v[104:105] op_sel:[0,1,0]
	v_pk_fma_f32 v[106:107], v[130:131], v[84:85], v[106:107] op_sel:[0,1,0]
	v_pk_fma_f32 v[108:109], v[132:133], v[84:85], v[108:109] op_sel:[0,1,0]
	v_pk_fma_f32 v[110:111], v[134:135], v[84:85], v[110:111] op_sel:[0,1,0]
	v_add_u32_e32 v16, v68, v160
	v_add_u32_e32 v20, v69, v160
	global_load_dwordx4 v[16:19], v16, s[42:43]
	global_load_dwordx4 v[20:23], v20, s[42:43]
	s_waitcnt vmcnt(16)
	v_cvt_pk_f32_fp8_e32 v[120:121], v24
	v_cvt_pk_f32_fp8_sdwa v[122:123], v24 src0_sel:WORD_1
	v_cvt_pk_f32_fp8_e32 v[124:125], v25
	v_cvt_pk_f32_fp8_sdwa v[126:127], v25 src0_sel:WORD_1
	v_pk_fma_f32 v[96:97], v[120:121], v[86:87], v[96:97] op_sel_hi:[1,0,1]
	v_pk_fma_f32 v[98:99], v[122:123], v[86:87], v[98:99] op_sel_hi:[1,0,1]
	v_pk_fma_f32 v[100:101], v[124:125], v[86:87], v[100:101] op_sel_hi:[1,0,1]
	v_pk_fma_f32 v[102:103], v[126:127], v[86:87], v[102:103] op_sel_hi:[1,0,1]
	v_cvt_pk_f32_fp8_e32 v[120:121], v26
	v_cvt_pk_f32_fp8_sdwa v[122:123], v26 src0_sel:WORD_1
	v_cvt_pk_f32_fp8_e32 v[124:125], v27
	v_cvt_pk_f32_fp8_sdwa v[126:127], v27 src0_sel:WORD_1
	v_pk_fma_f32 v[104:105], v[120:121], v[86:87], v[104:105] op_sel_hi:[1,0,1]
	v_pk_fma_f32 v[106:107], v[122:123], v[86:87], v[106:107] op_sel_hi:[1,0,1]
	v_pk_fma_f32 v[108:109], v[124:125], v[86:87], v[108:109] op_sel_hi:[1,0,1]
	v_pk_fma_f32 v[110:111], v[126:127], v[86:87], v[110:111] op_sel_hi:[1,0,1]
	v_cvt_pk_f32_fp8_e32 v[128:129], v28
	v_cvt_pk_f32_fp8_sdwa v[130:131], v28 src0_sel:WORD_1
	v_cvt_pk_f32_fp8_e32 v[132:133], v29
	v_cvt_pk_f32_fp8_sdwa v[134:135], v29 src0_sel:WORD_1
	v_pk_fma_f32 v[96:97], v[128:129], v[86:87], v[96:97] op_sel:[0,1,0]
	v_pk_fma_f32 v[98:99], v[130:131], v[86:87], v[98:99] op_sel:[0,1,0]
	v_pk_fma_f32 v[100:101], v[132:133], v[86:87], v[100:101] op_sel:[0,1,0]
	v_pk_fma_f32 v[102:103], v[134:135], v[86:87], v[102:103] op_sel:[0,1,0]
	v_cvt_pk_f32_fp8_e32 v[128:129], v30
	v_cvt_pk_f32_fp8_sdwa v[130:131], v30 src0_sel:WORD_1
	v_cvt_pk_f32_fp8_e32 v[132:133], v31
	v_cvt_pk_f32_fp8_sdwa v[134:135], v31 src0_sel:WORD_1
	v_pk_fma_f32 v[104:105], v[128:129], v[86:87], v[104:105] op_sel:[0,1,0]
	v_pk_fma_f32 v[106:107], v[130:131], v[86:87], v[106:107] op_sel:[0,1,0]
	v_pk_fma_f32 v[108:109], v[132:133], v[86:87], v[108:109] op_sel:[0,1,0]
	v_pk_fma_f32 v[110:111], v[134:135], v[86:87], v[110:111] op_sel:[0,1,0]
	v_add_u32_e32 v24, v70, v160
	v_add_u32_e32 v28, v71, v160
	global_load_dwordx4 v[24:27], v24, s[42:43]
	global_load_dwordx4 v[28:31], v28, s[42:43]
	s_waitcnt vmcnt(16)
	v_cvt_pk_f32_fp8_e32 v[120:121], v32
	v_cvt_pk_f32_fp8_sdwa v[122:123], v32 src0_sel:WORD_1
	v_cvt_pk_f32_fp8_e32 v[124:125], v33
	v_cvt_pk_f32_fp8_sdwa v[126:127], v33 src0_sel:WORD_1
	v_pk_fma_f32 v[96:97], v[120:121], v[88:89], v[96:97] op_sel_hi:[1,0,1]
	v_pk_fma_f32 v[98:99], v[122:123], v[88:89], v[98:99] op_sel_hi:[1,0,1]
	v_pk_fma_f32 v[100:101], v[124:125], v[88:89], v[100:101] op_sel_hi:[1,0,1]
	v_pk_fma_f32 v[102:103], v[126:127], v[88:89], v[102:103] op_sel_hi:[1,0,1]
	v_cvt_pk_f32_fp8_e32 v[120:121], v34
	v_cvt_pk_f32_fp8_sdwa v[122:123], v34 src0_sel:WORD_1
	v_cvt_pk_f32_fp8_e32 v[124:125], v35
	v_cvt_pk_f32_fp8_sdwa v[126:127], v35 src0_sel:WORD_1
	v_pk_fma_f32 v[104:105], v[120:121], v[88:89], v[104:105] op_sel_hi:[1,0,1]
	v_pk_fma_f32 v[106:107], v[122:123], v[88:89], v[106:107] op_sel_hi:[1,0,1]
	v_pk_fma_f32 v[108:109], v[124:125], v[88:89], v[108:109] op_sel_hi:[1,0,1]
	v_pk_fma_f32 v[110:111], v[126:127], v[88:89], v[110:111] op_sel_hi:[1,0,1]
	v_cvt_pk_f32_fp8_e32 v[128:129], v36
	v_cvt_pk_f32_fp8_sdwa v[130:131], v36 src0_sel:WORD_1
	v_cvt_pk_f32_fp8_e32 v[132:133], v37
	v_cvt_pk_f32_fp8_sdwa v[134:135], v37 src0_sel:WORD_1
	v_pk_fma_f32 v[96:97], v[128:129], v[88:89], v[96:97] op_sel:[0,1,0]
	v_pk_fma_f32 v[98:99], v[130:131], v[88:89], v[98:99] op_sel:[0,1,0]
	v_pk_fma_f32 v[100:101], v[132:133], v[88:89], v[100:101] op_sel:[0,1,0]
	v_pk_fma_f32 v[102:103], v[134:135], v[88:89], v[102:103] op_sel:[0,1,0]
	v_cvt_pk_f32_fp8_e32 v[128:129], v38
	v_cvt_pk_f32_fp8_sdwa v[130:131], v38 src0_sel:WORD_1
	v_cvt_pk_f32_fp8_e32 v[132:133], v39
	v_cvt_pk_f32_fp8_sdwa v[134:135], v39 src0_sel:WORD_1
	v_pk_fma_f32 v[104:105], v[128:129], v[88:89], v[104:105] op_sel:[0,1,0]
	v_pk_fma_f32 v[106:107], v[130:131], v[88:89], v[106:107] op_sel:[0,1,0]
	v_pk_fma_f32 v[108:109], v[132:133], v[88:89], v[108:109] op_sel:[0,1,0]
	v_pk_fma_f32 v[110:111], v[134:135], v[88:89], v[110:111] op_sel:[0,1,0]
	v_add_u32_e32 v32, v72, v160
	v_add_u32_e32 v36, v73, v160
	global_load_dwordx4 v[32:35], v32, s[42:43]
	global_load_dwordx4 v[36:39], v36, s[42:43]
	s_waitcnt vmcnt(16)
	v_cvt_pk_f32_fp8_e32 v[120:121], v40
	v_cvt_pk_f32_fp8_sdwa v[122:123], v40 src0_sel:WORD_1
	v_cvt_pk_f32_fp8_e32 v[124:125], v41
	v_cvt_pk_f32_fp8_sdwa v[126:127], v41 src0_sel:WORD_1
	v_pk_fma_f32 v[96:97], v[120:121], v[90:91], v[96:97] op_sel_hi:[1,0,1]
	v_pk_fma_f32 v[98:99], v[122:123], v[90:91], v[98:99] op_sel_hi:[1,0,1]
	v_pk_fma_f32 v[100:101], v[124:125], v[90:91], v[100:101] op_sel_hi:[1,0,1]
	v_pk_fma_f32 v[102:103], v[126:127], v[90:91], v[102:103] op_sel_hi:[1,0,1]
	v_cvt_pk_f32_fp8_e32 v[120:121], v42
	v_cvt_pk_f32_fp8_sdwa v[122:123], v42 src0_sel:WORD_1
	v_cvt_pk_f32_fp8_e32 v[124:125], v43
	v_cvt_pk_f32_fp8_sdwa v[126:127], v43 src0_sel:WORD_1
	v_pk_fma_f32 v[104:105], v[120:121], v[90:91], v[104:105] op_sel_hi:[1,0,1]
	v_pk_fma_f32 v[106:107], v[122:123], v[90:91], v[106:107] op_sel_hi:[1,0,1]
	v_pk_fma_f32 v[108:109], v[124:125], v[90:91], v[108:109] op_sel_hi:[1,0,1]
	v_pk_fma_f32 v[110:111], v[126:127], v[90:91], v[110:111] op_sel_hi:[1,0,1]
	v_cvt_pk_f32_fp8_e32 v[128:129], v44
	v_cvt_pk_f32_fp8_sdwa v[130:131], v44 src0_sel:WORD_1
	v_cvt_pk_f32_fp8_e32 v[132:133], v45
	v_cvt_pk_f32_fp8_sdwa v[134:135], v45 src0_sel:WORD_1
	v_pk_fma_f32 v[96:97], v[128:129], v[90:91], v[96:97] op_sel:[0,1,0]
	v_pk_fma_f32 v[98:99], v[130:131], v[90:91], v[98:99] op_sel:[0,1,0]
	v_pk_fma_f32 v[100:101], v[132:133], v[90:91], v[100:101] op_sel:[0,1,0]
	v_pk_fma_f32 v[102:103], v[134:135], v[90:91], v[102:103] op_sel:[0,1,0]
	v_cvt_pk_f32_fp8_e32 v[128:129], v46
	v_cvt_pk_f32_fp8_sdwa v[130:131], v46 src0_sel:WORD_1
	v_cvt_pk_f32_fp8_e32 v[132:133], v47
	v_cvt_pk_f32_fp8_sdwa v[134:135], v47 src0_sel:WORD_1
	v_pk_fma_f32 v[104:105], v[128:129], v[90:91], v[104:105] op_sel:[0,1,0]
	v_pk_fma_f32 v[106:107], v[130:131], v[90:91], v[106:107] op_sel:[0,1,0]
	v_pk_fma_f32 v[108:109], v[132:133], v[90:91], v[108:109] op_sel:[0,1,0]
	v_pk_fma_f32 v[110:111], v[134:135], v[90:91], v[110:111] op_sel:[0,1,0]
	v_add_u32_e32 v40, v74, v160
	v_add_u32_e32 v44, v75, v160
	global_load_dwordx4 v[40:43], v40, s[42:43]
	global_load_dwordx4 v[44:47], v44, s[42:43]
	s_waitcnt vmcnt(16)
	v_cvt_pk_f32_fp8_e32 v[120:121], v48
	v_cvt_pk_f32_fp8_sdwa v[122:123], v48 src0_sel:WORD_1
	v_cvt_pk_f32_fp8_e32 v[124:125], v49
	v_cvt_pk_f32_fp8_sdwa v[126:127], v49 src0_sel:WORD_1
	v_pk_fma_f32 v[96:97], v[120:121], v[92:93], v[96:97] op_sel_hi:[1,0,1]
	v_pk_fma_f32 v[98:99], v[122:123], v[92:93], v[98:99] op_sel_hi:[1,0,1]
	v_pk_fma_f32 v[100:101], v[124:125], v[92:93], v[100:101] op_sel_hi:[1,0,1]
	v_pk_fma_f32 v[102:103], v[126:127], v[92:93], v[102:103] op_sel_hi:[1,0,1]
	v_cvt_pk_f32_fp8_e32 v[120:121], v50
	v_cvt_pk_f32_fp8_sdwa v[122:123], v50 src0_sel:WORD_1
	v_cvt_pk_f32_fp8_e32 v[124:125], v51
	v_cvt_pk_f32_fp8_sdwa v[126:127], v51 src0_sel:WORD_1
	v_pk_fma_f32 v[104:105], v[120:121], v[92:93], v[104:105] op_sel_hi:[1,0,1]
	v_pk_fma_f32 v[106:107], v[122:123], v[92:93], v[106:107] op_sel_hi:[1,0,1]
	v_pk_fma_f32 v[108:109], v[124:125], v[92:93], v[108:109] op_sel_hi:[1,0,1]
	v_pk_fma_f32 v[110:111], v[126:127], v[92:93], v[110:111] op_sel_hi:[1,0,1]
	v_cvt_pk_f32_fp8_e32 v[128:129], v52
	v_cvt_pk_f32_fp8_sdwa v[130:131], v52 src0_sel:WORD_1
	v_cvt_pk_f32_fp8_e32 v[132:133], v53
	v_cvt_pk_f32_fp8_sdwa v[134:135], v53 src0_sel:WORD_1
	v_pk_fma_f32 v[96:97], v[128:129], v[92:93], v[96:97] op_sel:[0,1,0]
	v_pk_fma_f32 v[98:99], v[130:131], v[92:93], v[98:99] op_sel:[0,1,0]
	v_pk_fma_f32 v[100:101], v[132:133], v[92:93], v[100:101] op_sel:[0,1,0]
	v_pk_fma_f32 v[102:103], v[134:135], v[92:93], v[102:103] op_sel:[0,1,0]
	v_cvt_pk_f32_fp8_e32 v[128:129], v54
	v_cvt_pk_f32_fp8_sdwa v[130:131], v54 src0_sel:WORD_1
	v_cvt_pk_f32_fp8_e32 v[132:133], v55
	v_cvt_pk_f32_fp8_sdwa v[134:135], v55 src0_sel:WORD_1
	v_pk_fma_f32 v[104:105], v[128:129], v[92:93], v[104:105] op_sel:[0,1,0]
	v_pk_fma_f32 v[106:107], v[130:131], v[92:93], v[106:107] op_sel:[0,1,0]
	v_pk_fma_f32 v[108:109], v[132:133], v[92:93], v[108:109] op_sel:[0,1,0]
	v_pk_fma_f32 v[110:111], v[134:135], v[92:93], v[110:111] op_sel:[0,1,0]
	v_add_u32_e32 v48, v76, v160
	v_add_u32_e32 v52, v77, v160
	global_load_dwordx4 v[48:51], v48, s[42:43]
	global_load_dwordx4 v[52:55], v52, s[42:43]
	s_waitcnt vmcnt(16)
	v_cvt_pk_f32_fp8_e32 v[120:121], v56
	v_cvt_pk_f32_fp8_sdwa v[122:123], v56 src0_sel:WORD_1
	v_cvt_pk_f32_fp8_e32 v[124:125], v57
	v_cvt_pk_f32_fp8_sdwa v[126:127], v57 src0_sel:WORD_1
	v_pk_fma_f32 v[96:97], v[120:121], v[94:95], v[96:97] op_sel_hi:[1,0,1]
	v_pk_fma_f32 v[98:99], v[122:123], v[94:95], v[98:99] op_sel_hi:[1,0,1]
	v_pk_fma_f32 v[100:101], v[124:125], v[94:95], v[100:101] op_sel_hi:[1,0,1]
	v_pk_fma_f32 v[102:103], v[126:127], v[94:95], v[102:103] op_sel_hi:[1,0,1]
	v_cvt_pk_f32_fp8_e32 v[120:121], v58
	v_cvt_pk_f32_fp8_sdwa v[122:123], v58 src0_sel:WORD_1
	v_cvt_pk_f32_fp8_e32 v[124:125], v59
	v_cvt_pk_f32_fp8_sdwa v[126:127], v59 src0_sel:WORD_1
	v_pk_fma_f32 v[104:105], v[120:121], v[94:95], v[104:105] op_sel_hi:[1,0,1]
	v_pk_fma_f32 v[106:107], v[122:123], v[94:95], v[106:107] op_sel_hi:[1,0,1]
	v_pk_fma_f32 v[108:109], v[124:125], v[94:95], v[108:109] op_sel_hi:[1,0,1]
	v_pk_fma_f32 v[110:111], v[126:127], v[94:95], v[110:111] op_sel_hi:[1,0,1]
	v_cvt_pk_f32_fp8_e32 v[128:129], v60
	v_cvt_pk_f32_fp8_sdwa v[130:131], v60 src0_sel:WORD_1
	v_cvt_pk_f32_fp8_e32 v[132:133], v61
	v_cvt_pk_f32_fp8_sdwa v[134:135], v61 src0_sel:WORD_1
	v_pk_fma_f32 v[96:97], v[128:129], v[94:95], v[96:97] op_sel:[0,1,0]
	v_pk_fma_f32 v[98:99], v[130:131], v[94:95], v[98:99] op_sel:[0,1,0]
	v_pk_fma_f32 v[100:101], v[132:133], v[94:95], v[100:101] op_sel:[0,1,0]
	v_pk_fma_f32 v[102:103], v[134:135], v[94:95], v[102:103] op_sel:[0,1,0]
; DI int TID() { int t = threadIdx.x; asm volatile("" : "+v"(t)); return t; }
; DI void phase_norm(const Params& p, int l, int which, int bid, int nblk) {
;   const int lane = TID() & 63, w = TID() >> 6;
;   const float* g = (which ? p.in[I_G2] : p.in[I_G1]) + l * 1024;
;   const bool from_input = (which == 0 && l == 0);
;   for (int row = bid * 4 + w; row < ROWS; row += nblk * 4) {
;     const int b = row / TPB, pos = row % TPB;
;     if (which == 1 && l == 1 && pos < CTXL) continue;
;     const float* xr = xrow_ptr(p, from_input, b, pos);
;     const float* mod = WSP(const float, OFF_MOD) + (size_t)(l * 17 + (pos < CTXL ? 16 : b)) * 6144 + which * 3072;
; DI void phase_peer(const Params& p, int l, int bid, int nblk) {
;     ...
;     int row2 = row;
;     asm volatile("" : "+v"(row2));
;     const int lane2 = TID() & 63;
;     const int b2 = row2 / TPB, pos2 = row2 % TPB;
;     const float* xr = xrow_ptr(p, false, b2, pos2);
;     float* xw = xrow_wptr(p, b2, pos2);
;     const float* ga = WSP(const float, OFF_MOD) + (size_t)(l * 17 + (pos2 < CTXL ? 16 : b2)) * 6144 + 5120;
;     float xn[16];
;     float ss = 0.f;
; #pragma unroll
;     for (int q = 0; q < 4; ++q) {
;       const float4 xv = *(const float4*)(xr + lane2 * 16 + q * 4);
;       const float4 gv = *(const float4*)(ga + lane2 * 16 + q * 4);
;       xn[q * 4 + 0] = xv.x + gv.x * acc[q * 4 + 0];
;       xn[q * 4 + 1] = xv.y + gv.y * acc[q * 4 + 1];
;       xn[q * 4 + 2] = xv.z + gv.z * acc[q * 4 + 2];
;       xn[q * 4 + 3] = xv.w + gv.w * acc[q * 4 + 3];
;     }
;     if (l == 1) {
; #pragma unroll
;       for (int i = 0; i < 16; ++i) ss += xn[i] * xn[i];
;       ss = wave_sum(ss);
;       const float rs = rsqrtf(ss * (1.f / 1024.f) + EPSF);
; #pragma unroll
;       for (int i = 0; i < 16; ++i) xn[i] = xn[i] * rs * gfin[lane2 * 16 + i];
;     }
; #pragma unroll
;     for (int q = 0; q < 4; ++q) {
;       float4 o = {xn[q * 4 + 0], xn[q * 4 + 1], xn[q * 4 + 2], xn[q * 4 + 3]};
;       *(float4*)(xw + lane2 * 16 + q * 4) = o;
;     }
	v_cvt_pk_f32_fp8_e32 v[128:129], v62
	v_cvt_pk_f32_fp8_sdwa v[130:131], v62 src0_sel:WORD_1
	v_cvt_pk_f32_fp8_e32 v[132:133], v63
	v_cvt_pk_f32_fp8_sdwa v[134:135], v63 src0_sel:WORD_1
	v_pk_fma_f32 v[104:105], v[128:129], v[94:95], v[104:105] op_sel:[0,1,0]
	v_pk_fma_f32 v[106:107], v[130:131], v[94:95], v[106:107] op_sel:[0,1,0]
	v_pk_fma_f32 v[108:109], v[132:133], v[94:95], v[108:109] op_sel:[0,1,0]
	v_pk_fma_f32 v[110:111], v[134:135], v[94:95], v[110:111] op_sel:[0,1,0]
	v_add_u32_e32 v56, v78, v160
	v_add_u32_e32 v60, v79, v160
	global_load_dwordx4 v[56:59], v56, s[42:43]
	global_load_dwordx4 v[60:63], v60, s[42:43]
	s_nop 1
	v_permlane32_swap_b32 v96, v104
	v_permlane32_swap_b32 v97, v105
	v_permlane32_swap_b32 v98, v106
	v_permlane32_swap_b32 v99, v107
	v_permlane32_swap_b32 v100, v108
	v_permlane32_swap_b32 v101, v109
	v_permlane32_swap_b32 v102, v110
	v_permlane32_swap_b32 v103, v111
	v_pk_add_f32 v[96:97], v[96:97], v[104:105]
	v_pk_add_f32 v[98:99], v[98:99], v[106:107]
	v_pk_add_f32 v[100:101], v[100:101], v[108:109]
	v_pk_add_f32 v[102:103], v[102:103], v[110:111]
	s_nop 0
	v_permlane16_swap_b32 v96, v100
	v_permlane16_swap_b32 v97, v101
	v_permlane16_swap_b32 v98, v102
	v_permlane16_swap_b32 v99, v103
	v_pk_add_f32 v[96:97], v[96:97], v[100:101]
	v_pk_add_f32 v[98:99], v[98:99], v[102:103]
	v_cndmask_b32_e64 v120, v96, v98, s[40:41]
	v_cndmask_b32_e64 v121, v97, v99, s[40:41]
	v_cndmask_b32_e64 v122, v98, v96, s[40:41]
	v_cndmask_b32_e64 v123, v99, v97, s[40:41]
	s_nop 1
	v_add_f32_dpp v124, v122, v120 row_ror:8 row_mask:0xf bank_mask:0xf
	v_add_f32_dpp v125, v123, v121 row_ror:8 row_mask:0xf bank_mask:0xf
	s_waitcnt vmcnt(16)
	v_pk_fma_f32 v[140:141], v[142:143], v[124:125], v[140:141]
	s_nop 0
	global_store_dwordx2 v166, v[140:141], s[80:81]
	s_mov_b32 s46, s62
	s_mov_b32 s47, s63
	s_mov_b32 s48, s64
	s_mov_b32 s50, s65
	s_add_i32 s49, s49, -1
	s_cmp_lg_u32 s49, 0
	s_cbranch_scc1 .Lpeer_v_top
	s_waitcnt vmcnt(0) lgkmcnt(0)
	s_cmp_lg_u64 s[70:71], 0
	s_cbranch_scc1 .Lpeer_n1_done
	v_lshlrev_b32_e32 v144, 4, v161
	v_lshlrev_b32_e32 v149, 3, v161
	v_readlane_b32 s84, v253, 15
	v_readlane_b32 s85, v253, 16
	s_add_u32 s84, s84, 0x1000
	s_addc_u32 s85, s85, 0
	global_load_dwordx4 v[16:19], v144, s[84:85]
	global_load_dwordx4 v[20:23], v144, s[84:85] offset:1024
	global_load_dwordx4 v[24:27], v144, s[84:85] offset:2048
	global_load_dwordx4 v[28:31], v144, s[84:85] offset:3072
	v_xor_b32_e32 v145, 16, v161
	v_xor_b32_e32 v146, 32, v161
	v_lshlrev_b32_e32 v145, 2, v145
	v_lshlrev_b32_e32 v146, 2, v146
	s_mov_b32 s47, 0
.Lpeer_n1_top:
	s_cmp_ge_u32 s47, s55
	s_addc_u32 s48, s47, 0
	s_cmp_ge_u32 s48, s66
	s_addc_u32 s48, s48, 0
	s_lshl_b32 s48, s48, 11
	s_add_i32 s48, s48, s67
	s_mul_hi_u32 s13, s48, 0x38e38e39
	s_lshr_b32 s13, s13, 9
	s_mul_i32 s16, s13, 0x900
	s_sub_u32 s16, s48, s16
	s_cmp_lt_u32 s16, 0x100
	s_cbranch_scc1 .Lpeer_n1_ctx
	s_lshl_b32 s17, s13, 11
	s_add_i32 s17, s17, s16
	s_add_i32 s17, s17, 0xffffff00
	s_lshl_b32 s17, s17, 12
	s_add_u32 s80, s94, s17
	s_addc_u32 s81, s95, 0
	s_add_i32 s13, s13, 17
	s_branch .Lpeer_n1_ptr
.Lpeer_n1_ctx:
	s_lshl_b32 s17, s13, 8
	s_add_i32 s17, s17, s16
	s_lshl_b32 s17, s17, 12
	s_add_u32 s80, s96, 0x17a00000
	s_addc_u32 s81, s97, 0
	s_add_u32 s80, s80, s17
	s_addc_u32 s81, s81, 0
	s_movk_i32 s13, 33
; DI int TID() { int t = threadIdx.x; asm volatile("" : "+v"(t)); return t; }
; DI u32 pack2(float a, float b) { return (u32)f2bf(a) | ((u32)f2bf(b) << 16); }
; DI void phase_norm(const Params& p, int l, int which, int bid, int nblk) {
;   const int lane = TID() & 63, w = TID() >> 6;
;   const float* g = (which ? p.in[I_G2] : p.in[I_G1]) + l * 1024;
;   const bool from_input = (which == 0 && l == 0);
;   for (int row = bid * 4 + w; row < ROWS; row += nblk * 4) {
;     const int b = row / TPB, pos = row % TPB;
;     if (which == 1 && l == 1 && pos < CTXL) continue;
;     const float* xr = xrow_ptr(p, from_input, b, pos);
;     const float* mod = WSP(const float, OFF_MOD) + (size_t)(l * 17 + (pos < CTXL ? 16 : b)) * 6144 + which * 3072;
;     float x[16];
; #pragma unroll
;     for (int hh = 0; hh < 2; ++hh) {
;       const float4 a = *(const float4*)(xr + hh * 512 + lane * 8);
;       const float4 c = *(const float4*)(xr + hh * 512 + lane * 8 + 4);
;       x[hh * 8 + 0] = a.x; x[hh * 8 + 1] = a.y; x[hh * 8 + 2] = a.z; x[hh * 8 + 3] = a.w;
;       x[hh * 8 + 4] = c.x; x[hh * 8 + 5] = c.y; x[hh * 8 + 6] = c.z; x[hh * 8 + 7] = c.w;
;     }
;     float ss = 0.f;
; #pragma unroll
;     for (int i = 0; i < 16; ++i) ss += x[i] * x[i];
;     ss = wave_sum(ss);
;     const float rs = rsqrtf(ss * (1.f / 1024.f) + EPSF);
; #pragma unroll
;     for (int hh = 0; hh < 2; ++hh) {
;       const int c0 = hh * 512 + lane * 8;
;       float y[8];
; #pragma unroll
;       for (int i = 0; i < 8; ++i) {
;         const float yn = x[hh * 8 + i] * rs * g[c0 + i];
;         y[i] = yn * (1.f + mod[1024 + c0 + i]) + mod[c0 + i];
;       }
;       uint4 o = {pack2(y[0], y[1]), pack2(y[2], y[3]), pack2(y[4], y[5]), pack2(y[6], y[7])};
;       *(uint4*)&WSP(u16, OFF_ACT)[(size_t)row * 1024 + c0] = o;
;     }
;   }
; }
.Lpeer_n1_ptr:
	s_mul_i32 s13, s13, 0x6000
	s_add_u32 s82, s96, 0x1be04000
	s_addc_u32 s83, s97, 0
	s_add_u32 s82, s82, s13
	s_addc_u32 s83, s83, 0
	s_add_u32 s78, s82, 0x1000
	s_addc_u32 s79, s83, 0
	s_lshl_b32 s17, s48, 11
	s_add_u32 s84, s6, s17
	s_addc_u32 s85, s7, 0
	global_load_dwordx4 v[32:35], v144, s[80:81] sc1
	global_load_dwordx4 v[36:39], v144, s[80:81] offset:1024 sc1
	global_load_dwordx4 v[40:43], v144, s[80:81] offset:2048 sc1
	global_load_dwordx4 v[44:47], v144, s[80:81] offset:3072 sc1
	global_load_dwordx4 v[48:51], v144, s[82:83]
	global_load_dwordx4 v[52:55], v144, s[82:83] offset:1024
	global_load_dwordx4 v[56:59], v144, s[82:83] offset:2048
	global_load_dwordx4 v[60:63], v144, s[82:83] offset:3072
	global_load_dwordx4 v[64:67], v144, s[78:79]
	global_load_dwordx4 v[68:71], v144, s[78:79] offset:1024
	global_load_dwordx4 v[72:75], v144, s[78:79] offset:2048
	global_load_dwordx4 v[76:79], v144, s[78:79] offset:3072
	s_waitcnt vmcnt(8)
	v_mul_f32_e32 v147, v32, v32
	v_fmac_f32_e32 v147, v33, v33
	v_fmac_f32_e32 v147, v34, v34
	v_fmac_f32_e32 v147, v35, v35
	v_fmac_f32_e32 v147, v36, v36
	v_fmac_f32_e32 v147, v37, v37
	v_fmac_f32_e32 v147, v38, v38
	v_fmac_f32_e32 v147, v39, v39
	v_fmac_f32_e32 v147, v40, v40
	v_fmac_f32_e32 v147, v41, v41
	v_fmac_f32_e32 v147, v42, v42
	v_fmac_f32_e32 v147, v43, v43
	v_fmac_f32_e32 v147, v44, v44
	v_fmac_f32_e32 v147, v45, v45
	v_fmac_f32_e32 v147, v46, v46
	v_fmac_f32_e32 v147, v47, v47
	s_nop 1
	v_add_f32_dpp v147, v147, v147 quad_perm:[1,0,3,2] row_mask:0xf bank_mask:0xf
	s_nop 1
	v_add_f32_dpp v147, v147, v147 quad_perm:[2,3,0,1] row_mask:0xf bank_mask:0xf
	s_nop 1
	v_add_f32_dpp v147, v147, v147 row_half_mirror row_mask:0xf bank_mask:0xf
	s_nop 1
	v_add_f32_dpp v147, v147, v147 row_mirror row_mask:0xf bank_mask:0xf
	s_nop 1
	ds_bpermute_b32 v148, v145, v147
	s_waitcnt lgkmcnt(0)
	v_add_f32_e32 v147, v147, v148
	ds_bpermute_b32 v148, v146, v147
	s_waitcnt lgkmcnt(0)
	v_add_f32_e32 v147, v147, v148
	v_mov_b32_e32 v148, 0x358637bd
	v_fmac_f32_e32 v148, 0x3a800000, v147
	v_rsq_f32_e32 v148, v148
	s_waitcnt vmcnt(0)
	v_mul_f32_e32 v32, v32, v148
	v_mul_f32_e32 v33, v33, v148
	v_mul_f32_e32 v34, v34, v148
	v_mul_f32_e32 v35, v35, v148
	v_mul_f32_e32 v36, v36, v148
	v_mul_f32_e32 v37, v37, v148
	v_mul_f32_e32 v38, v38, v148
	v_mul_f32_e32 v39, v39, v148
	v_mul_f32_e32 v40, v40, v148
	v_mul_f32_e32 v41, v41, v148
	v_mul_f32_e32 v42, v42, v148
	v_mul_f32_e32 v43, v43, v148
	v_mul_f32_e32 v44, v44, v148
	v_mul_f32_e32 v45, v45, v148
	v_mul_f32_e32 v46, v46, v148
	v_mul_f32_e32 v47, v47, v148
	v_mul_f32_e32 v32, v32, v16
	v_mul_f32_e32 v33, v33, v17
	v_mul_f32_e32 v34, v34, v18
	v_mul_f32_e32 v35, v35, v19
	v_mul_f32_e32 v36, v36, v20
	v_mul_f32_e32 v37, v37, v21
	v_mul_f32_e32 v38, v38, v22
	v_mul_f32_e32 v39, v39, v23
	v_mul_f32_e32 v40, v40, v24
	v_mul_f32_e32 v41, v41, v25
	v_mul_f32_e32 v42, v42, v26
	v_mul_f32_e32 v43, v43, v27
	v_mul_f32_e32 v44, v44, v28
	v_mul_f32_e32 v45, v45, v29
	v_mul_f32_e32 v46, v46, v30
	v_mul_f32_e32 v47, v47, v31
	v_add_f32_e32 v64, 1.0, v64
	v_add_f32_e32 v65, 1.0, v65
	v_add_f32_e32 v66, 1.0, v66
	v_add_f32_e32 v67, 1.0, v67
	v_add_f32_e32 v68, 1.0, v68
	v_add_f32_e32 v69, 1.0, v69
	v_add_f32_e32 v70, 1.0, v70
	v_add_f32_e32 v71, 1.0, v71
	v_add_f32_e32 v72, 1.0, v72
	v_add_f32_e32 v73, 1.0, v73
	v_add_f32_e32 v74, 1.0, v74
	v_add_f32_e32 v75, 1.0, v75
	v_add_f32_e32 v76, 1.0, v76
	v_add_f32_e32 v77, 1.0, v77
	v_add_f32_e32 v78, 1.0, v78
	v_add_f32_e32 v79, 1.0, v79
	v_fma_f32 v32, v32, v64, v48
	v_fma_f32 v33, v33, v65, v49
	v_fma_f32 v34, v34, v66, v50
	v_fma_f32 v35, v35, v67, v51
	v_fma_f32 v36, v36, v68, v52
	v_fma_f32 v37, v37, v69, v53
	v_fma_f32 v38, v38, v70, v54
	v_fma_f32 v39, v39, v71, v55
	v_fma_f32 v40, v40, v72, v56
	v_fma_f32 v41, v41, v73, v57
	v_fma_f32 v42, v42, v74, v58
	v_fma_f32 v43, v43, v75, v59
	v_fma_f32 v44, v44, v76, v60
	v_fma_f32 v45, v45, v77, v61
	v_fma_f32 v46, v46, v78, v62
	v_fma_f32 v47, v47, v79, v63
	v_cvt_pk_bf16_f32 v32, v32, v33
	v_cvt_pk_bf16_f32 v33, v34, v35
	v_cvt_pk_bf16_f32 v34, v36, v37
	v_cvt_pk_bf16_f32 v35, v38, v39
	v_cvt_pk_bf16_f32 v36, v40, v41
	v_cvt_pk_bf16_f32 v37, v42, v43
	v_cvt_pk_bf16_f32 v38, v44, v45
	v_cvt_pk_bf16_f32 v39, v46, v47
	s_nop 0
	global_store_dwordx2 v149, v[32:33], s[84:85]
	global_store_dwordx2 v149, v[34:35], s[84:85] offset:512
	global_store_dwordx2 v149, v[36:37], s[84:85] offset:1024
	global_store_dwordx2 v149, v[38:39], s[84:85] offset:1536
	s_add_i32 s47, s47, 1
	s_cmp_lt_u32 s47, s75
	s_cbranch_scc1 .Lpeer_n1_top
.Lpeer_n1_done:
	s_cmp_eq_u64 s[70:71], 0
	s_cbranch_scc1 .Lpeer_e_done
	v_lshlrev_b32_e32 v144, 4, v161
	global_load_dwordx4 v[16:19], v144, s[92:93]
	global_load_dwordx4 v[20:23], v144, s[92:93] offset:1024
	global_load_dwordx4 v[24:27], v144, s[92:93] offset:2048
	global_load_dwordx4 v[28:31], v144, s[92:93] offset:3072
	v_xor_b32_e32 v145, 16, v161
	v_xor_b32_e32 v146, 32, v161
	v_lshlrev_b32_e32 v145, 2, v145
	v_lshlrev_b32_e32 v146, 2, v146
	s_mov_b32 s47, 0
